# accumulator zeroing at every GEMM unit start with v_mov_b64 pairs (64 instead of 128 instructions per wave)
# speedup vs baseline: 1.0232x; 1.0087x over previous
.LBB0_709:
	s_ashr_i32 s17, s16, 31
	s_lshl_b64 s[18:19], s[16:17], 19
	v_readlane_b32 s20, v251, 20
	v_readlane_b32 s21, v251, 21
	s_add_u32 s18, s20, s18
	s_addc_u32 s19, s21, s19
	s_and_b64 s[20:21], s[6:7], exec
	s_cselect_b32 s1, s19, s3
	s_cselect_b32 s17, s18, s2
	s_ashr_i32 s15, s14, 31
	s_lshl_b64 s[20:21], s[14:15], 19
	s_add_u32 s20, s26, s20
	s_addc_u32 s21, s27, s21
	s_and_b64 s[24:25], s[6:7], exec
	s_cselect_b32 s15, s21, s23
	s_cselect_b32 s40, s20, s22
	s_add_u32 s2, s2, 0x40080
	s_addc_u32 s3, s3, 0
	s_add_u32 s41, s22, 0x100
	v_mov_b32_e32 v0, 0
	s_addc_u32 s42, s23, 0
	s_mov_b32 s43, -2
	v_mov_b32_e32 v1, 0
	v_mov_b64_e32 v[2:3], 0
	v_mov_b64_e32 v[4:5], 0
	v_mov_b64_e32 v[6:7], 0
	v_mov_b64_e32 v[8:9], 0
	v_mov_b64_e32 v[10:11], 0
	v_mov_b64_e32 v[12:13], 0
	v_mov_b64_e32 v[14:15], 0
	v_mov_b64_e32 v[16:17], 0
	v_mov_b64_e32 v[18:19], 0
	v_mov_b64_e32 v[20:21], 0
	v_mov_b64_e32 v[22:23], 0
	v_mov_b64_e32 v[24:25], 0
	v_mov_b64_e32 v[26:27], 0
	v_mov_b64_e32 v[28:29], 0
	v_mov_b64_e32 v[30:31], 0
	v_mov_b64_e32 v[32:33], 0
	v_mov_b64_e32 v[34:35], 0
	v_mov_b64_e32 v[36:37], 0
	v_mov_b64_e32 v[38:39], 0
	v_mov_b64_e32 v[40:41], 0
	v_mov_b64_e32 v[42:43], 0
	v_mov_b64_e32 v[44:45], 0
	v_mov_b64_e32 v[46:47], 0
	v_mov_b64_e32 v[48:49], 0
	v_mov_b64_e32 v[50:51], 0
	v_mov_b64_e32 v[52:53], 0
	v_mov_b64_e32 v[54:55], 0
	v_mov_b64_e32 v[56:57], 0
	v_mov_b64_e32 v[58:59], 0
	v_mov_b64_e32 v[60:61], 0
	v_mov_b64_e32 v[62:63], 0
	v_mov_b64_e32 v[64:65], 0
	v_mov_b64_e32 v[66:67], 0
	v_mov_b64_e32 v[68:69], 0
	v_mov_b64_e32 v[70:71], 0
	v_mov_b64_e32 v[72:73], 0
	v_mov_b64_e32 v[74:75], 0
	v_mov_b64_e32 v[76:77], 0
	v_mov_b64_e32 v[78:79], 0
	v_mov_b64_e32 v[80:81], 0
	v_mov_b64_e32 v[82:83], 0
	v_mov_b64_e32 v[84:85], 0
	v_mov_b64_e32 v[86:87], 0
	v_mov_b64_e32 v[88:89], 0
	v_mov_b64_e32 v[90:91], 0
	v_mov_b64_e32 v[92:93], 0
	v_mov_b64_e32 v[94:95], 0
	v_mov_b64_e32 v[98:99], 0
	v_mov_b64_e32 v[100:101], 0
	v_mov_b64_e32 v[102:103], 0
	v_mov_b64_e32 v[104:105], 0
	v_mov_b64_e32 v[106:107], 0
	v_mov_b64_e32 v[108:109], 0
	v_mov_b64_e32 v[110:111], 0
	v_mov_b64_e32 v[112:113], 0
	v_mov_b64_e32 v[114:115], 0
	v_mov_b64_e32 v[116:117], 0
	v_mov_b64_e32 v[118:119], 0
	v_mov_b64_e32 v[120:121], 0
	v_mov_b64_e32 v[122:123], 0
	v_mov_b64_e32 v[124:125], 0
	v_mov_b64_e32 v[126:127], 0
	v_mov_b64_e32 v[128:129], 0

.LBB0_767:
	s_ashr_i32 s15, s14, 31
	s_lshl_b64 s[16:17], s[14:15], 19
	v_readlane_b32 s18, v251, 20
	v_readlane_b32 s19, v251, 21
	s_add_u32 s16, s18, s16
	s_addc_u32 s17, s19, s17
	s_and_b64 s[18:19], s[4:5], exec
	s_cselect_b32 s15, s17, s3
	s_cselect_b32 s38, s16, s2
	s_ashr_i32 s13, s12, 31
	s_lshl_b64 s[18:19], s[12:13], 19
	s_add_u32 s18, s24, s18
	s_addc_u32 s19, s25, s19
	s_and_b64 s[22:23], s[4:5], exec
	s_cselect_b32 s13, s19, s21
	s_cselect_b32 s39, s18, s20
	s_add_u32 s2, s2, 0x40080
	s_addc_u32 s3, s3, 0
	s_add_u32 s40, s20, 0x100
	v_mov_b32_e32 v0, 0
	s_addc_u32 s41, s21, 0
	s_mov_b32 s42, -2
	v_mov_b32_e32 v1, 0
	v_mov_b64_e32 v[2:3], 0
	v_mov_b64_e32 v[4:5], 0
	v_mov_b64_e32 v[6:7], 0
	v_mov_b64_e32 v[8:9], 0
	v_mov_b64_e32 v[10:11], 0
	v_mov_b64_e32 v[12:13], 0
	v_mov_b64_e32 v[14:15], 0
	v_mov_b64_e32 v[16:17], 0
	v_mov_b64_e32 v[18:19], 0
	v_mov_b64_e32 v[20:21], 0
	v_mov_b64_e32 v[22:23], 0
	v_mov_b64_e32 v[24:25], 0
	v_mov_b64_e32 v[26:27], 0
	v_mov_b64_e32 v[28:29], 0
	v_mov_b64_e32 v[30:31], 0
	v_mov_b64_e32 v[32:33], 0
	v_mov_b64_e32 v[34:35], 0
	v_mov_b64_e32 v[36:37], 0
	v_mov_b64_e32 v[38:39], 0
	v_mov_b64_e32 v[40:41], 0
	v_mov_b64_e32 v[42:43], 0
	v_mov_b64_e32 v[44:45], 0
	v_mov_b64_e32 v[46:47], 0
	v_mov_b64_e32 v[48:49], 0
	v_mov_b64_e32 v[50:51], 0
	v_mov_b64_e32 v[52:53], 0
	v_mov_b64_e32 v[54:55], 0
	v_mov_b64_e32 v[56:57], 0
	v_mov_b64_e32 v[58:59], 0
	v_mov_b64_e32 v[60:61], 0
	v_mov_b64_e32 v[62:63], 0
	v_mov_b64_e32 v[64:65], 0
	v_mov_b64_e32 v[66:67], 0
	v_mov_b64_e32 v[68:69], 0
	v_mov_b64_e32 v[70:71], 0
	v_mov_b64_e32 v[72:73], 0
	v_mov_b64_e32 v[74:75], 0
	v_mov_b64_e32 v[76:77], 0
	v_mov_b64_e32 v[78:79], 0
	v_mov_b64_e32 v[80:81], 0
	v_mov_b64_e32 v[82:83], 0
	v_mov_b64_e32 v[84:85], 0
	v_mov_b64_e32 v[86:87], 0
	v_mov_b64_e32 v[88:89], 0
	v_mov_b64_e32 v[90:91], 0
	v_mov_b64_e32 v[92:93], 0
	v_mov_b64_e32 v[94:95], 0
	v_mov_b64_e32 v[98:99], 0
	v_mov_b64_e32 v[100:101], 0
	v_mov_b64_e32 v[102:103], 0
	v_mov_b64_e32 v[104:105], 0
	v_mov_b64_e32 v[106:107], 0
	v_mov_b64_e32 v[108:109], 0
	v_mov_b64_e32 v[110:111], 0
	v_mov_b64_e32 v[112:113], 0
	v_mov_b64_e32 v[114:115], 0
	v_mov_b64_e32 v[116:117], 0
	v_mov_b64_e32 v[118:119], 0
	v_mov_b64_e32 v[120:121], 0
	v_mov_b64_e32 v[122:123], 0
	v_mov_b64_e32 v[124:125], 0
	v_mov_b64_e32 v[126:127], 0
	v_mov_b64_e32 v[128:129], 0

.LBB0_799:
	s_ashr_i32 s21, s20, 31
	s_lshl_b64 s[22:23], s[20:21], 19
	v_readlane_b32 s24, v251, 24
	v_readlane_b32 s25, v251, 25
	s_add_u32 s22, s24, s22
	s_addc_u32 s23, s25, s23
	s_and_b64 s[24:25], s[8:9], exec
	s_cselect_b32 s1, s23, s3
	s_cselect_b32 s11, s22, s2
	s_ashr_i32 s19, s18, 31
	s_lshl_b64 s[24:25], s[18:19], 19
	s_add_u32 s24, s30, s24
	s_addc_u32 s25, s31, s25
	s_and_b64 s[28:29], s[8:9], exec
	s_cselect_b32 s19, s25, s27
	s_cselect_b32 s21, s24, s26
	s_add_u32 s2, s2, 0x40080
	s_addc_u32 s3, s3, 0
	s_add_u32 s44, s26, 0x100
	v_mov_b32_e32 v0, 0
	s_addc_u32 s45, s27, 0
	s_mov_b32 s46, -2
	v_mov_b32_e32 v1, 0
	v_mov_b64_e32 v[2:3], 0
	v_mov_b64_e32 v[4:5], 0
	v_mov_b64_e32 v[6:7], 0
	v_mov_b64_e32 v[8:9], 0
	v_mov_b64_e32 v[10:11], 0
	v_mov_b64_e32 v[12:13], 0
	v_mov_b64_e32 v[14:15], 0
	v_mov_b64_e32 v[16:17], 0
	v_mov_b64_e32 v[18:19], 0
	v_mov_b64_e32 v[20:21], 0
	v_mov_b64_e32 v[22:23], 0
	v_mov_b64_e32 v[24:25], 0
	v_mov_b64_e32 v[26:27], 0
	v_mov_b64_e32 v[28:29], 0
	v_mov_b64_e32 v[30:31], 0
	v_mov_b64_e32 v[32:33], 0
	v_mov_b64_e32 v[34:35], 0
	v_mov_b64_e32 v[36:37], 0
	v_mov_b64_e32 v[38:39], 0
	v_mov_b64_e32 v[40:41], 0
	v_mov_b64_e32 v[42:43], 0
	v_mov_b64_e32 v[44:45], 0
	v_mov_b64_e32 v[46:47], 0
	v_mov_b64_e32 v[48:49], 0
	v_mov_b64_e32 v[50:51], 0
	v_mov_b64_e32 v[52:53], 0
	v_mov_b64_e32 v[54:55], 0
	v_mov_b64_e32 v[56:57], 0
	v_mov_b64_e32 v[58:59], 0
	v_mov_b64_e32 v[60:61], 0
	v_mov_b64_e32 v[62:63], 0
	v_mov_b64_e32 v[64:65], 0
	v_mov_b64_e32 v[66:67], 0
	v_mov_b64_e32 v[68:69], 0
	v_mov_b64_e32 v[70:71], 0
	v_mov_b64_e32 v[72:73], 0
	v_mov_b64_e32 v[74:75], 0
	v_mov_b64_e32 v[76:77], 0
	v_mov_b64_e32 v[78:79], 0
	v_mov_b64_e32 v[80:81], 0
	v_mov_b64_e32 v[82:83], 0
	v_mov_b64_e32 v[84:85], 0
	v_mov_b64_e32 v[86:87], 0
	v_mov_b64_e32 v[88:89], 0
	v_mov_b64_e32 v[90:91], 0
	v_mov_b64_e32 v[92:93], 0
	v_mov_b64_e32 v[94:95], 0
	v_mov_b64_e32 v[98:99], 0
	v_mov_b64_e32 v[100:101], 0
	v_mov_b64_e32 v[102:103], 0
	v_mov_b64_e32 v[104:105], 0
	v_mov_b64_e32 v[106:107], 0
	v_mov_b64_e32 v[108:109], 0
	v_mov_b64_e32 v[110:111], 0
	v_mov_b64_e32 v[112:113], 0
	v_mov_b64_e32 v[114:115], 0
	v_mov_b64_e32 v[116:117], 0
	v_mov_b64_e32 v[118:119], 0
	v_mov_b64_e32 v[120:121], 0
	v_mov_b64_e32 v[122:123], 0
	v_mov_b64_e32 v[124:125], 0
	v_mov_b64_e32 v[126:127], 0
	v_mov_b64_e32 v[128:129], 0

.LBB0_943:
	s_add_u32 s61, s0, s41
	s_addc_u32 s62, s1, s40
	s_add_u32 s63, s2, 0x100
	v_mov_b32_e32 v0, 0
	s_addc_u32 s64, s3, 0
	s_mov_b64 s[2:3], 0
	v_mov_b32_e32 v1, 0
	v_mov_b64_e32 v[2:3], 0
	v_mov_b64_e32 v[4:5], 0
	v_mov_b64_e32 v[6:7], 0
	v_mov_b64_e32 v[8:9], 0
	v_mov_b64_e32 v[10:11], 0
	v_mov_b64_e32 v[12:13], 0
	v_mov_b64_e32 v[14:15], 0
	v_mov_b64_e32 v[16:17], 0
	v_mov_b64_e32 v[18:19], 0
	v_mov_b64_e32 v[20:21], 0
	v_mov_b64_e32 v[22:23], 0
	v_mov_b64_e32 v[24:25], 0
	v_mov_b64_e32 v[26:27], 0
	v_mov_b64_e32 v[28:29], 0
	v_mov_b64_e32 v[30:31], 0
	v_mov_b64_e32 v[32:33], 0
	v_mov_b64_e32 v[34:35], 0
	v_mov_b64_e32 v[36:37], 0
	v_mov_b64_e32 v[38:39], 0
	v_mov_b64_e32 v[40:41], 0
	v_mov_b64_e32 v[42:43], 0
	v_mov_b64_e32 v[44:45], 0
	v_mov_b64_e32 v[46:47], 0
	v_mov_b64_e32 v[48:49], 0
	v_mov_b64_e32 v[50:51], 0
	v_mov_b64_e32 v[52:53], 0
	v_mov_b64_e32 v[54:55], 0
	v_mov_b64_e32 v[56:57], 0
	v_mov_b64_e32 v[58:59], 0
	v_mov_b64_e32 v[60:61], 0
	v_mov_b64_e32 v[62:63], 0
	v_mov_b64_e32 v[64:65], 0
	v_mov_b64_e32 v[66:67], 0
	v_mov_b64_e32 v[68:69], 0
	v_mov_b64_e32 v[70:71], 0
	v_mov_b64_e32 v[72:73], 0
	v_mov_b64_e32 v[74:75], 0
	v_mov_b64_e32 v[76:77], 0
	v_mov_b64_e32 v[78:79], 0
	v_mov_b64_e32 v[80:81], 0
	v_mov_b64_e32 v[82:83], 0
	v_mov_b64_e32 v[84:85], 0
	v_mov_b64_e32 v[86:87], 0
	v_mov_b64_e32 v[88:89], 0
	v_mov_b64_e32 v[90:91], 0
	v_mov_b64_e32 v[92:93], 0
	v_mov_b64_e32 v[94:95], 0
	v_mov_b64_e32 v[98:99], 0
	v_mov_b64_e32 v[100:101], 0
	v_mov_b64_e32 v[102:103], 0
	v_mov_b64_e32 v[104:105], 0
	v_mov_b64_e32 v[106:107], 0
	v_mov_b64_e32 v[108:109], 0
	v_mov_b64_e32 v[110:111], 0
	v_mov_b64_e32 v[112:113], 0
	v_mov_b64_e32 v[114:115], 0
	v_mov_b64_e32 v[116:117], 0
	v_mov_b64_e32 v[118:119], 0
	v_mov_b64_e32 v[120:121], 0
	v_mov_b64_e32 v[122:123], 0
	v_mov_b64_e32 v[124:125], 0
	v_mov_b64_e32 v[126:127], 0
	v_mov_b64_e32 v[128:129], 0

.LBB0_1130:
	s_ashr_i32 s15, s14, 31
	s_lshl_b64 s[16:17], s[14:15], 19
	v_readlane_b32 s18, v251, 20
	v_readlane_b32 s19, v251, 21
	s_add_u32 s16, s18, s16
	s_addc_u32 s17, s19, s17
	s_and_b64 s[18:19], s[4:5], exec
	s_cselect_b32 s15, s17, s3
	s_cselect_b32 s39, s16, s2
	s_ashr_i32 s13, s12, 31
	s_lshl_b64 s[18:19], s[12:13], 19
	s_add_u32 s18, s24, s18
	s_addc_u32 s19, s25, s19
	s_and_b64 s[22:23], s[4:5], exec
	s_cselect_b32 s13, s19, s21
	s_cselect_b32 s40, s18, s20
	s_add_u32 s2, s2, 0x40080
	s_addc_u32 s3, s3, 0
	s_add_u32 s41, s20, 0x100
	v_mov_b32_e32 v0, 0
	s_addc_u32 s42, s21, 0
	s_mov_b32 s43, -2
	v_mov_b32_e32 v1, 0
	v_mov_b64_e32 v[2:3], 0
	v_mov_b64_e32 v[4:5], 0
	v_mov_b64_e32 v[6:7], 0
	v_mov_b64_e32 v[8:9], 0
	v_mov_b64_e32 v[10:11], 0
	v_mov_b64_e32 v[12:13], 0
	v_mov_b64_e32 v[14:15], 0
	v_mov_b64_e32 v[16:17], 0
	v_mov_b64_e32 v[18:19], 0
	v_mov_b64_e32 v[20:21], 0
	v_mov_b64_e32 v[22:23], 0
	v_mov_b64_e32 v[24:25], 0
	v_mov_b64_e32 v[26:27], 0
	v_mov_b64_e32 v[28:29], 0
	v_mov_b64_e32 v[30:31], 0
	v_mov_b64_e32 v[32:33], 0
	v_mov_b64_e32 v[34:35], 0
	v_mov_b64_e32 v[36:37], 0
	v_mov_b64_e32 v[38:39], 0
	v_mov_b64_e32 v[40:41], 0
	v_mov_b64_e32 v[42:43], 0
	v_mov_b64_e32 v[44:45], 0
	v_mov_b64_e32 v[46:47], 0
	v_mov_b64_e32 v[48:49], 0
	v_mov_b64_e32 v[50:51], 0
	v_mov_b64_e32 v[52:53], 0
	v_mov_b64_e32 v[54:55], 0
	v_mov_b64_e32 v[56:57], 0
	v_mov_b64_e32 v[58:59], 0
	v_mov_b64_e32 v[60:61], 0
	v_mov_b64_e32 v[62:63], 0
	v_mov_b64_e32 v[64:65], 0
	v_mov_b64_e32 v[66:67], 0
	v_mov_b64_e32 v[68:69], 0
	v_mov_b64_e32 v[70:71], 0
	v_mov_b64_e32 v[72:73], 0
	v_mov_b64_e32 v[74:75], 0
	v_mov_b64_e32 v[76:77], 0
	v_mov_b64_e32 v[78:79], 0
	v_mov_b64_e32 v[80:81], 0
	v_mov_b64_e32 v[82:83], 0
	v_mov_b64_e32 v[84:85], 0
	v_mov_b64_e32 v[86:87], 0
	v_mov_b64_e32 v[88:89], 0
	v_mov_b64_e32 v[90:91], 0
	v_mov_b64_e32 v[92:93], 0
	v_mov_b64_e32 v[94:95], 0
	v_mov_b64_e32 v[98:99], 0
	v_mov_b64_e32 v[100:101], 0
	v_mov_b64_e32 v[102:103], 0
	v_mov_b64_e32 v[104:105], 0
	v_mov_b64_e32 v[106:107], 0
	v_mov_b64_e32 v[108:109], 0
	v_mov_b64_e32 v[110:111], 0
	v_mov_b64_e32 v[112:113], 0
	v_mov_b64_e32 v[114:115], 0
	v_mov_b64_e32 v[116:117], 0
	v_mov_b64_e32 v[118:119], 0
	v_mov_b64_e32 v[120:121], 0
	v_mov_b64_e32 v[122:123], 0
	v_mov_b64_e32 v[124:125], 0
	v_mov_b64_e32 v[126:127], 0
	v_mov_b64_e32 v[128:129], 0
